# v59 + grid barriers: XCD leader completes its L2 invalidate before releasing the XCD; the other workgroups of that XCD only invalidate their L1 (sc0)
# speedup vs baseline: 1.0247x; 1.0045x over previous
; __device__ __forceinline__ unsigned xb_ld(unsigned* p)              { return __hip_atomic_load(p, __ATOMIC_RELAXED, __HIP_MEMORY_SCOPE_AGENT); }
; __device__ __forceinline__ unsigned xb_add(unsigned* p, unsigned v) { return __hip_atomic_fetch_add(p, v, __ATOMIC_RELAXED, __HIP_MEMORY_SCOPE_AGENT); }
; #define XB_SPIN(cond, bar) do { unsigned _sp = 0; while (cond) { __builtin_amdgcn_s_sleep(1); \
;     if ((++_sp & 255u) == 0u) { if (xb_ld(&(bar)[XB_TMO])) break; if (_sp > XB_SPIN_CAP) { atomicAdd(&(bar)[XB_TMO], 1u); break; } } } } while (0)
; __device__ __forceinline__ void xcd_barrier(const XcdBarrier& b) {
;     ...
;         const unsigned old = xb_add(&bar[XB_XSUB(b.x)], 1u);
;         const unsigned gen = old / nloc;
;         if (old + 1u == (gen + 1u) * nloc) {
;             __builtin_amdgcn_fence(__ATOMIC_RELEASE, "agent");
;             asm volatile("s_waitcnt vmcnt(0)" ::: "memory");
;             const unsigned og = xb_add(&bar[XB_TOP], 1u);
;             const unsigned tg = og / nx;
;             if (og + 1u == (tg + 1u) * nx) xb_add(&bar[XB_TOPGEN], 1u);
;             else XB_SPIN(xb_ld(&bar[XB_TOPGEN]) == tg, bar);
;             __builtin_amdgcn_fence(__ATOMIC_ACQUIRE, "agent");
;             xb_add(&bar[XB_XGEN(b.x)], 1u);
;             asm volatile("s_waitcnt vmcnt(0)" ::: "memory");
;         } else {
;             XB_SPIN(xb_ld(&bar[XB_XGEN(b.x)]) == gen, bar);
;             __builtin_amdgcn_fence(__ATOMIC_ACQUIRE, "agent");
;             asm volatile("s_waitcnt vmcnt(0)" ::: "memory");
;         }
.LBB0_161:
	s_or_b64 exec, exec, s[28:29]
	s_waitcnt vmcnt(0)
	buffer_inv sc0
	s_waitcnt vmcnt(0)

; __device__ __forceinline__ unsigned xb_ld(unsigned* p)              { return __hip_atomic_load(p, __ATOMIC_RELAXED, __HIP_MEMORY_SCOPE_AGENT); }
; __device__ __forceinline__ unsigned xb_add(unsigned* p, unsigned v) { return __hip_atomic_fetch_add(p, v, __ATOMIC_RELAXED, __HIP_MEMORY_SCOPE_AGENT); }
; #define XB_SPIN(cond, bar) do { unsigned _sp = 0; while (cond) { __builtin_amdgcn_s_sleep(1); \
;     if ((++_sp & 255u) == 0u) { if (xb_ld(&(bar)[XB_TMO])) break; if (_sp > XB_SPIN_CAP) { atomicAdd(&(bar)[XB_TMO], 1u); break; } } } } while (0)
; __device__ __forceinline__ void xcd_barrier(const XcdBarrier& b) {
;     ...
;             const unsigned og = xb_add(&bar[XB_TOP], 1u);
;             const unsigned tg = og / nx;
;             if (og + 1u == (tg + 1u) * nx) xb_add(&bar[XB_TOPGEN], 1u);
;             else XB_SPIN(xb_ld(&bar[XB_TOPGEN]) == tg, bar);
;             __builtin_amdgcn_fence(__ATOMIC_ACQUIRE, "agent");
;             xb_add(&bar[XB_XGEN(b.x)], 1u);
;             asm volatile("s_waitcnt vmcnt(0)" ::: "memory");
.LBB0_179:
	s_or_b64 exec, exec, s[6:7]
	v_mov_b32_e32 v1, 0x2000
	v_mov_b32_e32 v2, 1
	s_waitcnt vmcnt(0)
	buffer_inv sc1
	s_waitcnt vmcnt(0)
	global_atomic_add v1, v2, s[4:5] offset:1024
	s_waitcnt vmcnt(0)

; __device__ __forceinline__ unsigned xb_ld(unsigned* p)              { return __hip_atomic_load(p, __ATOMIC_RELAXED, __HIP_MEMORY_SCOPE_AGENT); }
; #define XB_SPIN(cond, bar) do { unsigned _sp = 0; while (cond) { __builtin_amdgcn_s_sleep(1); \
;     if ((++_sp & 255u) == 0u) { if (xb_ld(&(bar)[XB_TMO])) break; if (_sp > XB_SPIN_CAP) { atomicAdd(&(bar)[XB_TMO], 1u); break; } } } } while (0)
; __device__ __forceinline__ void xcd_barrier(const XcdBarrier& b) {
;     ...
;         } else {
;             XB_SPIN(xb_ld(&bar[XB_XGEN(b.x)]) == gen, bar);
;             __builtin_amdgcn_fence(__ATOMIC_ACQUIRE, "agent");
;             asm volatile("s_waitcnt vmcnt(0)" ::: "memory");
;         }
.LBB0_558:
	s_or_b64 exec, exec, s[8:9]
	s_waitcnt vmcnt(0)
	buffer_inv sc0
	s_waitcnt vmcnt(0)
